# NA QK block: all eight K-fragment reads issued up front into unused registers with counted waits (on top of the MLA eight-deep QK)
# speedup vs baseline: 1.0182x; 1.0031x over previous
; __device__ __forceinline__ void finishSM(f32x16& p0, f32x16& p1, float alpha, float& l_reg, bf16x8& pa0, bf16x8& pa1, bf16x8& pa2, bf16x8& pa3) {
; #pragma unroll
;   for (int r = 0; r < 16; ++r) p1[r] = __builtin_amdgcn_exp2f(p1[r]);
;   float ps = 0;
; #pragma unroll
;   for (int r = 0; r < 16; ++r) ps += p0[r];
; #pragma unroll
;   for (int r = 0; r < 16; ++r) ps += p1[r];
;   { auto rr = __builtin_amdgcn_permlane32_swap(__float_as_uint(ps), __float_as_uint(ps), false, false);
;     ps = __uint_as_float(rr[0]) + __uint_as_float(rr[1]); }
;   l_reg = l_reg * alpha + ps;
;     ...
;   PK4(p0, 0, pa0); PK4(p0, 8, pa1); PK4(p1, 0, pa2); PK4(p1, 8, pa3);
;     ...
; }
; template <int DQK> __device__ __forceinline__ void qkt(f32x16& p0, f32x16& p1, const char* Ks, const bf16x8* qr, int r32, int hi) {
;   p0 = f32x16{}; p1 = f32x16{};
; #pragma unroll
;   for (int d0 = 0; d0 < DQK / 16; ++d0) { int cb = (d0 * 16 + hi * 8) * 2;
;     bf16x8 b0 = *reinterpret_cast<const bf16x8*>(Ks + KSWZ(r32, cb));
;     bf16x8 b1 = *reinterpret_cast<const bf16x8*>(Ks + KSWZ(32 + r32, cb));
;     p0 = __builtin_amdgcn_mfma_f32_32x32x16_bf16(b0, qr[d0], p0, 0, 0, 0);
;     p1 = __builtin_amdgcn_mfma_f32_32x32x16_bf16(b1, qr[d0], p1, 0, 0, 0); }
; }
; __device__ __forceinline__ int v_st(int k, int c) { const int kk = (k & ~0xC) | ((k & 4) << 1) | ((k & 8) >> 1); return ((kk >> 3) * 4 + (c >> 5)) * 512 + ((kk & 7) * 32 + (c & 31)) * 2; }
; __device__ __forceinline__ int v_rd_base(int lane) { return ((lane & 3) << 3) | (((lane >> 2) & 3) << 6) | (((lane >> 4) & 1) << 5) | (((lane >> 5) & 1) << 8); }
; template <int OFF> __device__ __forceinline__ s16x4 tr_read(int vb) {
;   s16x4 r; asm volatile("ds_read_b64_tr_b16 %0, %1 offset:%2" : "=&v"(r) : "v"(vb), "i"(OFF) : "memory"); return r;
; }
; template <int D0> __device__ __forceinline__ void pv_one(f32x16& od, int vb, bf16x8 pa0, bf16x8 pa1, bf16x8 pa2, bf16x8 pa3) {
;   const s16x4 l0 = tr_read<v_rd_off(D0, 0, 0)>(vb), h0 = tr_read<v_rd_off(D0, 0, 1)>(vb), l1 = tr_read<v_rd_off(D0, 1, 0)>(vb), h1 = tr_read<v_rd_off(D0, 1, 1)>(vb);
; template <int DQK, int MODE, int ldq, int ldk, int ldv> ...
;     ...
;     SBAR(); qkt<DQK>(pB0, pB1, K_lds + SHM_K, qr, r32, hi);
;     finishSM(pA0, pA1, alA, l_reg, pa0, pa1, pa2, pa3); SBAR();
;     SLOAD(SO, j + 2); SBAR();
;     pv_d0(o, vb0, pa0, pa1, pa2, pa3); BIAS(pB0, pB1, j); partialSM<DQK>(pB0, pB1, m_reg, mnB, alB);
.LBB0_781:
	ds_read_b128 v[32:35], v134 offset:49152
	ds_read_b128 v[36:39], v134 offset:57344
	ds_read_b128 v[156:159], v135 offset:49152
	ds_read_b128 v[160:163], v135 offset:57344
	ds_read_b128 v[168:171], v136 offset:49152
	ds_read_b128 v[172:175], v136 offset:57344
	ds_read_b128 v[176:179], v137 offset:49152
	ds_read_b128 v[180:183], v137 offset:57344
	v_exp_f32_e32 v155, v96
	v_add_f32_e32 v96, 0, v152
	s_waitcnt lgkmcnt(7)
	v_mfma_f32_32x32x16_bf16 v[48:63], v[32:35], v[76:79], 0
	v_add_f32_e32 v96, v154, v96
	v_add_f32_e32 v96, v150, v96
	v_add_f32_e32 v96, v153, v96
	v_add_f32_e32 v96, v148, v96
	v_add_f32_e32 v96, v151, v96
	v_add_f32_e32 v96, v147, v96
	v_add_f32_e32 v96, v149, v96
	s_waitcnt lgkmcnt(6)
	v_mfma_f32_32x32x16_bf16 v[32:47], v[36:39], v[76:79], 0
	v_add_f32_e32 v96, v111, v96
	v_add_f32_e32 v96, v146, v96
	v_add_f32_e32 v96, v109, v96
	v_add_f32_e32 v96, v143, v96
	v_exp_f32_e32 v105, v102
	v_add_f32_e32 v96, v107, v96
	v_exp_f32_e32 v142, v103
	s_waitcnt lgkmcnt(5)
	v_mfma_f32_32x32x16_bf16 v[48:63], v[156:159], v[72:75], v[48:63]
	v_add_f32_e32 v96, v110, v96
	v_exp_f32_e32 v144, v100
	v_add_f32_e32 v96, v106, v96
	v_exp_f32_e32 v145, v101
	v_add_f32_e32 v96, v108, v96
	v_add_f32_e32 v96, v105, v96
	v_add_f32_e32 v96, v142, v96
	s_waitcnt lgkmcnt(4)
	v_mfma_f32_32x32x16_bf16 v[32:47], v[160:163], v[72:75], v[32:47]
	v_exp_f32_e32 v92, v92
	v_add_f32_e32 v96, v144, v96
	v_exp_f32_e32 v93, v93
	v_add_f32_e32 v96, v145, v96
	v_exp_f32_e32 v88, v88
	v_add_f32_e32 v96, v155, v96
	s_waitcnt lgkmcnt(3)
	v_mfma_f32_32x32x16_bf16 v[48:63], v[168:171], v[68:71], v[48:63]
	v_exp_f32_e32 v89, v89
	v_exp_f32_e32 v94, v94
	v_exp_f32_e32 v95, v95
	v_exp_f32_e32 v90, v90
	v_exp_f32_e32 v91, v91
	s_waitcnt lgkmcnt(2)
	v_mfma_f32_32x32x16_bf16 v[32:47], v[172:175], v[68:71], v[32:47]
	s_waitcnt lgkmcnt(1)
	v_mfma_f32_32x32x16_bf16 v[48:63], v[176:179], v[64:67], v[48:63]
	v_exp_f32_e32 v156, v97
	v_exp_f32_e32 v157, v98
	v_exp_f32_e32 v158, v99
	v_add_f32_e32 v96, v156, v96
	v_add_f32_e32 v96, v92, v96
	v_add_f32_e32 v96, v93, v96
	v_add_f32_e32 v96, v88, v96
	v_add_f32_e32 v96, v89, v96
	s_waitcnt lgkmcnt(0)
	v_mfma_f32_32x32x16_bf16 v[32:47], v[180:183], v[64:67], v[32:47]
	v_add_f32_e32 v96, v157, v96
	v_add_f32_e32 v96, v158, v96
	v_add_f32_e32 v96, v94, v96
	v_add_f32_e32 v96, v95, v96
	v_add_f32_e32 v96, v90, v96
	v_add_f32_e32 v140, v91, v96
	v_mov_b32_e32 v141, v140
	s_nop 1
	v_permlane32_swap_b32_e32 v140, v141
	v_cvt_pk_bf16_f32 v96, v152, v154
	v_cvt_pk_bf16_f32 v97, v150, v153
	v_cvt_pk_bf16_f32 v98, v148, v151
	v_cvt_pk_bf16_f32 v99, v147, v149
	v_cvt_pk_bf16_f32 v100, v111, v146
	v_cvt_pk_bf16_f32 v101, v109, v143
	v_cvt_pk_bf16_f32 v102, v107, v110
	v_cvt_pk_bf16_f32 v103, v106, v108
	v_cvt_pk_bf16_f32 v106, v105, v142
	v_cvt_pk_bf16_f32 v107, v144, v145
	v_cvt_pk_bf16_f32 v108, v155, v156
	v_cvt_pk_bf16_f32 v109, v92, v93
	v_cvt_pk_bf16_f32 v142, v88, v89
	v_cvt_pk_bf16_f32 v143, v157, v158
	v_cvt_pk_bf16_f32 v144, v94, v95
	v_cvt_pk_bf16_f32 v145, v90, v91
	s_nop 0
	v_permlane32_swap_b32_e32 v96, v98
	v_permlane32_swap_b32_e32 v97, v99
	v_permlane32_swap_b32_e32 v100, v102
	v_permlane32_swap_b32_e32 v101, v103
	v_permlane32_swap_b32_e32 v106, v108
	v_permlane32_swap_b32_e32 v107, v109
	v_permlane32_swap_b32_e32 v142, v144
	v_permlane32_swap_b32_e32 v143, v145
	s_sub_i32 s0, s78, 64
	s_cmp_lt_u32 s3, 2
	s_cselect_b32 s0, s76, s0
	s_ashr_i32 s1, s0, 31
	v_lshl_add_u64 v[88:89], s[0:1], 0, v[114:115]
	v_mad_u64_u32 v[90:91], s[0:1], v88, s86, v[116:117]
	v_mad_u64_u32 v[92:93], s[0:1], v88, s86, v[118:119]
	v_mad_i32_i24 v91, v89, s86, v91
	v_mad_i32_i24 v93, v89, s86, v93
	global_load_dwordx4 v[88:91], v[90:91], off
	s_nop 0
	global_load_dwordx4 v[92:95], v[92:93], off
	ds_read_b64_tr_b16 v[146:147], v128 offset:0
	ds_read_b64_tr_b16 v[148:149], v128 offset:0x800
	ds_read_b64_tr_b16 v[150:151], v128 offset:0x1000
	ds_read_b64_tr_b16 v[152:153], v128 offset:0x1800
	ds_read_b64_tr_b16 v[154:155], v128 offset:0x2000
	ds_read_b64_tr_b16 v[156:157], v128 offset:0x2800
	ds_read_b64_tr_b16 v[158:159], v128 offset:0x3000
	ds_read_b64_tr_b16 v[160:161], v128 offset:0x3800
	s_waitcnt lgkmcnt(0)
	s_nop 0
	v_mfma_f32_32x32x16_bf16 v[0:15], v[96:99], v[146:149], v[0:15]
	ds_read_b64_tr_b16 v[146:147], v128 offset:0x200
	ds_read_b64_tr_b16 v[148:149], v128 offset:0xa00
	v_mfma_f32_32x32x16_bf16 v[0:15], v[100:103], v[150:153], v[0:15]
	ds_read_b64_tr_b16 v[150:151], v128 offset:0x1200
	ds_read_b64_tr_b16 v[152:153], v128 offset:0x1a00
	v_mfma_f32_32x32x16_bf16 v[0:15], v[106:109], v[154:157], v[0:15]
	ds_read_b64_tr_b16 v[154:155], v128 offset:0x2200
	ds_read_b64_tr_b16 v[156:157], v128 offset:0x2a00
	v_mfma_f32_32x32x16_bf16 v[0:15], v[142:145], v[158:161], v[0:15]
	ds_read_b64_tr_b16 v[158:159], v128 offset:0x3200
	ds_read_b64_tr_b16 v[160:161], v128 offset:0x3a00
	s_waitcnt lgkmcnt(0)
	v_mfma_f32_32x32x16_bf16 v[16:31], v[96:99], v[146:149], v[16:31]
	v_mfma_f32_32x32x16_bf16 v[16:31], v[100:103], v[150:153], v[16:31]
	v_mfma_f32_32x32x16_bf16 v[16:31], v[106:109], v[154:157], v[16:31]
	v_mfma_f32_32x32x16_bf16 v[16:31], v[142:145], v[158:161], v[16:31]
	s_cmp_lt_u32 s3, 4
	s_cbranch_scc1 .LBB0_817
; #define SBAR() __builtin_amdgcn_sched_barrier(0)
; __device__ __forceinline__ void na_bias(f32x16& p0, f32x16& p1, const NaInfo& na, int kr, int hi) {
;   const int rs = min(max(na.qr - 4, 0), 120);
;   if (kr < rs || kr >= rs + 8) {
; #pragma unroll
;     for (int r = 0; r < 16; ++r) { p0[r] = -1e30f; p1[r] = -1e30f; }
;   } else {
;     const float* b = na.brow + (kr - na.qr + 7) * 31 + (15 - na.qc) + 4 * hi;
;     const int ws = min(max(na.qc - 8, 0), 48) - 4 * hi;
; #pragma unroll
;     for (int r = 0; r < 16; ++r) {
;       const int kc0 = (r & 3) + 8 * (r >> 2);
;       const bool ok1 = (unsigned)(kc0 - ws) < 16u, ok2 = (unsigned)(kc0 + 32 - ws) < 16u;
;       const float b1 = b[kc0], b2 = b[kc0 + 32];
;       p0[r] = ok1 ? p0[r] + 8.0f * b1 : -1e30f;
;       p1[r] = ok2 ? p1[r] + 8.0f * b2 : -1e30f;
;       if ((r & 3) == 3) SBAR();
;     }
;   }
; }
	s_add_i32 s0, s2, s3
	s_add_i32 s0, s0, -4
	v_cmp_ge_i32_e32 vcc, s0, v130
	v_cmp_lt_i32_e64 s[0:1], s0, v131
	s_and_b64 s[80:81], vcc, s[0:1]
	s_and_saveexec_b64 s[0:1], s[80:81]
	ds_read_b32 v142, v139
	ds_read_b32 v143, v139 offset:4
	ds_read_b32 v110, v139 offset:8
	ds_read_b32 v111, v139 offset:12
	ds_read_b32 v107, v139 offset:32
	ds_read_b32 v108, v139 offset:36
	ds_read_b32 v105, v139 offset:40
	ds_read_b32 v106, v139 offset:44
	ds_read_b32 v102, v139 offset:64
	ds_read_b32 v103, v139 offset:68
	ds_read_b32 v100, v139 offset:72
	ds_read_b32 v101, v139 offset:76
	ds_read_b32 v98, v139 offset:96
	ds_read_b32 v99, v139 offset:100
	ds_read_b32 v96, v139 offset:104
	ds_read_b32 v97, v139 offset:108
	ds_read_b32 v158, v139 offset:128
	ds_read_b32 v109, v139 offset:132
	ds_read_b32 v144, v139 offset:136
	ds_read_b32 v145, v139 offset:140
	ds_read_b32 v146, v139 offset:160
	ds_read_b32 v147, v139 offset:164
	ds_read_b32 v148, v139 offset:168
	ds_read_b32 v149, v139 offset:172
	ds_read_b32 v150, v139 offset:192
	ds_read_b32 v151, v139 offset:196
	ds_read_b32 v152, v139 offset:200
	ds_read_b32 v153, v139 offset:204
	ds_read_b32 v154, v139 offset:224
	ds_read_b32 v155, v139 offset:228
	ds_read_b32 v156, v139 offset:232
	ds_read_b32 v157, v139 offset:236
	s_or_b64 exec, exec, s[0:1]
	s_waitcnt lgkmcnt(0)
	s_and_b64 vcc, s[70:71], s[80:81]
	v_fmamk_f32 v142, v142, 0x41000000, v48
	v_cndmask_b32_e32 v48, v248, v142, vcc
	s_and_b64 s[0:1], s[68:69], s[80:81]
	v_fmamk_f32 v143, v143, 0x41000000, v49
	v_cndmask_b32_e64 v49, v248, v143, s[0:1]
	s_and_b64 vcc, s[66:67], s[80:81]
	v_fmamk_f32 v110, v110, 0x41000000, v50
	v_cndmask_b32_e32 v50, v248, v110, vcc
	s_and_b64 s[0:1], s[64:65], s[80:81]
	v_fmamk_f32 v111, v111, 0x41000000, v51
	v_cndmask_b32_e64 v51, v248, v111, s[0:1]
	s_and_b64 vcc, s[62:63], s[80:81]
	v_fmamk_f32 v107, v107, 0x41000000, v52
	v_cndmask_b32_e32 v52, v248, v107, vcc
	s_and_b64 s[0:1], s[60:61], s[80:81]
	v_fmamk_f32 v108, v108, 0x41000000, v53
	v_cndmask_b32_e64 v53, v248, v108, s[0:1]
	s_and_b64 vcc, s[58:59], s[80:81]
	v_fmamk_f32 v105, v105, 0x41000000, v54
	v_cndmask_b32_e32 v54, v248, v105, vcc
	s_and_b64 s[0:1], s[56:57], s[80:81]
	v_fmamk_f32 v106, v106, 0x41000000, v55
	v_cndmask_b32_e64 v55, v248, v106, s[0:1]
	s_and_b64 vcc, s[54:55], s[80:81]
	v_fmamk_f32 v102, v102, 0x41000000, v56
	v_cndmask_b32_e32 v56, v248, v102, vcc
	s_and_b64 s[0:1], s[52:53], s[80:81]
	v_fmamk_f32 v103, v103, 0x41000000, v57
	v_cndmask_b32_e64 v57, v248, v103, s[0:1]
	s_and_b64 vcc, s[50:51], s[80:81]
	v_fmamk_f32 v100, v100, 0x41000000, v58
	v_cndmask_b32_e32 v58, v248, v100, vcc
	s_and_b64 s[0:1], s[48:49], s[80:81]
	v_fmamk_f32 v101, v101, 0x41000000, v59
	v_cndmask_b32_e64 v59, v248, v101, s[0:1]
	s_and_b64 vcc, s[46:47], s[80:81]
	v_fmamk_f32 v98, v98, 0x41000000, v60
	v_cndmask_b32_e32 v60, v248, v98, vcc
	s_and_b64 s[0:1], s[44:45], s[80:81]
	v_fmamk_f32 v99, v99, 0x41000000, v61
	v_cndmask_b32_e64 v61, v248, v99, s[0:1]
	s_and_b64 vcc, s[42:43], s[80:81]
	v_fmamk_f32 v96, v96, 0x41000000, v62
	v_cndmask_b32_e32 v62, v248, v96, vcc
	s_and_b64 s[0:1], s[40:41], s[80:81]
	v_fmamk_f32 v97, v97, 0x41000000, v63
	v_cndmask_b32_e64 v63, v248, v97, s[0:1]
	s_and_b64 vcc, s[6:7], s[80:81]
	v_fmamk_f32 v158, v158, 0x41000000, v32
	v_cndmask_b32_e32 v32, v248, v158, vcc
	s_and_b64 s[0:1], s[8:9], s[80:81]
	v_fmamk_f32 v109, v109, 0x41000000, v33
	v_cndmask_b32_e64 v33, v248, v109, s[0:1]
	s_and_b64 vcc, s[10:11], s[80:81]
	v_fmamk_f32 v144, v144, 0x41000000, v34
	v_cndmask_b32_e32 v34, v248, v144, vcc
	s_and_b64 s[0:1], s[12:13], s[80:81]
	v_fmamk_f32 v145, v145, 0x41000000, v35
	v_cndmask_b32_e64 v35, v248, v145, s[0:1]
	s_and_b64 vcc, s[14:15], s[80:81]
	v_fmamk_f32 v146, v146, 0x41000000, v36
	v_cndmask_b32_e32 v36, v248, v146, vcc
	s_and_b64 s[0:1], s[16:17], s[80:81]
	v_fmamk_f32 v147, v147, 0x41000000, v37
	v_cndmask_b32_e64 v37, v248, v147, s[0:1]
	s_and_b64 vcc, s[18:19], s[80:81]
	v_fmamk_f32 v148, v148, 0x41000000, v38
	v_cndmask_b32_e32 v38, v248, v148, vcc
	s_and_b64 s[0:1], s[20:21], s[80:81]
	v_fmamk_f32 v149, v149, 0x41000000, v39
	v_cndmask_b32_e64 v39, v248, v149, s[0:1]
	s_and_b64 vcc, s[22:23], s[80:81]
	v_fmamk_f32 v150, v150, 0x41000000, v40
	v_cndmask_b32_e32 v40, v248, v150, vcc
	s_and_b64 s[0:1], s[24:25], s[80:81]
	v_fmamk_f32 v151, v151, 0x41000000, v41
	v_cndmask_b32_e64 v41, v248, v151, s[0:1]
	s_and_b64 vcc, s[26:27], s[80:81]
	v_fmamk_f32 v152, v152, 0x41000000, v42
	v_cndmask_b32_e32 v42, v248, v152, vcc
	s_and_b64 s[0:1], s[28:29], s[80:81]
	v_fmamk_f32 v153, v153, 0x41000000, v43
	v_cndmask_b32_e64 v43, v248, v153, s[0:1]
	s_and_b64 vcc, s[30:31], s[80:81]
	v_fmamk_f32 v154, v154, 0x41000000, v44
	v_cndmask_b32_e32 v44, v248, v154, vcc
	s_and_b64 s[0:1], s[34:35], s[80:81]
	v_fmamk_f32 v155, v155, 0x41000000, v45
	v_cndmask_b32_e64 v45, v248, v155, s[0:1]
	s_and_b64 vcc, s[36:37], s[80:81]
	v_fmamk_f32 v156, v156, 0x41000000, v46
	v_cndmask_b32_e32 v46, v248, v156, vcc
	s_and_b64 s[0:1], s[38:39], s[80:81]
	v_fmamk_f32 v157, v157, 0x41000000, v47
	v_cndmask_b32_e64 v47, v248, v157, s[0:1]

; template <int DQK> __device__ __forceinline__ void partialSM(f32x16& p0, f32x16& p1, float& m_reg, float& mn, float& alpha) {
;   constexpr float SCALE = (DQK == 96) ? 0.10206207261596577f : 0.125f;
;   constexpr float C = SCALE * 1.4426950408889634f;
;   float pmax = p0[0];
; #pragma unroll
;   for (int r = 1; r < 16; ++r) pmax = fmaxf(pmax, p0[r]);
; #pragma unroll
;   for (int r = 0; r < 16; ++r) pmax = fmaxf(pmax, p1[r]);
;   { auto rr = __builtin_amdgcn_permlane32_swap(__float_as_uint(pmax), __float_as_uint(pmax), false, false);
;     pmax = fmaxf(__uint_as_float(rr[0]), __uint_as_float(rr[1])); }
;   if (__builtin_expect(__all(pmax - m_reg <= THR / SCALE), 1)) { mn = m_reg; alpha = 1.f; }
;   else { mn = fmaxf(m_reg, pmax); alpha = __builtin_amdgcn_exp2f((m_reg - mn) * C); m_reg = mn; }
;   float mnC = -mn * C;
; #pragma unroll
;   for (int r = 0; r < 16; ++r) p0[r] = fmaf(p0[r], C, mnC);
; #pragma unroll
;   for (int r = 0; r < 16; ++r) p1[r] = fmaf(p1[r], C, mnC);
; #pragma unroll
;   for (int r = 0; r < 16; ++r) p0[r] = __builtin_amdgcn_exp2f(p0[r]);
; }
; __device__ __forceinline__ void finishSM(f32x16& p0, f32x16& p1, float alpha, float& l_reg, bf16x8& pa0, bf16x8& pa1, bf16x8& pa2, bf16x8& pa3) {
; #pragma unroll
;   for (int r = 0; r < 16; ++r) p1[r] = __builtin_amdgcn_exp2f(p1[r]);
;   float ps = 0;
; #pragma unroll
;   for (int r = 0; r < 16; ++r) ps += p0[r];
; #pragma unroll
;   for (int r = 0; r < 16; ++r) ps += p1[r];
;   { auto rr = __builtin_amdgcn_permlane32_swap(__float_as_uint(ps), __float_as_uint(ps), false, false);
;     ps = __uint_as_float(rr[0]) + __uint_as_float(rr[1]); }
;   l_reg = l_reg * alpha + ps;
;     ...
;   PK4(p0, 0, pa0); PK4(p0, 8, pa1); PK4(p1, 0, pa2); PK4(p1, 8, pa3);
;     ...
; }
; template <int DQK> __device__ __forceinline__ void qkt(f32x16& p0, f32x16& p1, const char* Ks, const bf16x8* qr, int r32, int hi) {
;   p0 = f32x16{}; p1 = f32x16{};
; #pragma unroll
;   for (int d0 = 0; d0 < DQK / 16; ++d0) { int cb = (d0 * 16 + hi * 8) * 2;
; template <int DQK, int MODE, int ldq, int ldk, int ldv> ...
;     ...
;     SBAR(); qkt<DQK>(pA0, pA1, K_lds, qr, r32, hi);
;     finishSM(pB0, pB1, alB, l_reg, pa0, pa1, pa2, pa3); SBAR();
;     if (j + 3 < NT) SLOAD(SE, j + 3); SBAR();
;     pv_d0(o, vb0 + (int)SHM_V, pa0, pa1, pa2, pa3); BIAS(pA0, pA1, j + 1); partialSM<DQK>(pA0, pA1, m_reg, mnA, alA);
.LBB0_821:
	v_cndmask_b32_e64 v143, v96, v104, s[0:1]
	v_mul_f32_e32 v144, 0xbe38aa3b, v143
	v_fmamk_f32 v48, v48, 0x3e38aa3b, v144
	v_fmamk_f32 v49, v49, 0x3e38aa3b, v144
	v_fmamk_f32 v50, v50, 0x3e38aa3b, v144
	v_fmamk_f32 v51, v51, 0x3e38aa3b, v144
	v_fmamk_f32 v52, v52, 0x3e38aa3b, v144
	v_fmamk_f32 v53, v53, 0x3e38aa3b, v144
	v_fmamk_f32 v54, v54, 0x3e38aa3b, v144
	v_fmamk_f32 v55, v55, 0x3e38aa3b, v144
	v_fmamk_f32 v56, v56, 0x3e38aa3b, v144
	v_fmamk_f32 v57, v57, 0x3e38aa3b, v144
	v_fmamk_f32 v58, v58, 0x3e38aa3b, v144
	v_fmamk_f32 v59, v59, 0x3e38aa3b, v144
	v_fmamk_f32 v60, v60, 0x3e38aa3b, v144
	v_fmamk_f32 v61, v61, 0x3e38aa3b, v144
	v_fmamk_f32 v62, v62, 0x3e38aa3b, v144
	v_fmamk_f32 v63, v63, 0x3e38aa3b, v144
	v_exp_f32_e32 v96, v48
	v_exp_f32_e32 v111, v49
	v_exp_f32_e32 v97, v50
	v_exp_f32_e32 v110, v51
	v_exp_f32_e32 v98, v52
	v_exp_f32_e32 v109, v53
	v_exp_f32_e32 v99, v54
	v_exp_f32_e32 v108, v55
	v_exp_f32_e32 v100, v56
	v_exp_f32_e32 v107, v57
	v_exp_f32_e32 v101, v58
	v_exp_f32_e32 v106, v59
	v_exp_f32_e32 v102, v60
	v_exp_f32_e32 v105, v61
	v_exp_f32_e32 v103, v62
	v_exp_f32_e32 v104, v63
	v_fmamk_f32 v153, v32, 0x3e38aa3b, v144
	v_fmamk_f32 v154, v33, 0x3e38aa3b, v144
	v_fmamk_f32 v155, v34, 0x3e38aa3b, v144
	v_fmamk_f32 v156, v35, 0x3e38aa3b, v144
	v_fmamk_f32 v157, v36, 0x3e38aa3b, v144
	v_fmamk_f32 v146, v37, 0x3e38aa3b, v144
	v_fmamk_f32 v147, v38, 0x3e38aa3b, v144
	v_fmamk_f32 v148, v39, 0x3e38aa3b, v144
	v_fmamk_f32 v149, v40, 0x3e38aa3b, v144
	v_fmamk_f32 v150, v41, 0x3e38aa3b, v144
	v_fmamk_f32 v151, v42, 0x3e38aa3b, v144
	v_fmamk_f32 v152, v43, 0x3e38aa3b, v144
	v_fmamk_f32 v145, v44, 0x3e38aa3b, v144
	v_fmamk_f32 v158, v45, 0x3e38aa3b, v144
	v_fmamk_f32 v159, v46, 0x3e38aa3b, v144
	v_fmac_f32_e32 v144, 0x3e38aa3b, v47
	s_waitcnt lgkmcnt(0)
	s_barrier
	ds_read_b128 v[32:35], v134 offset:32768
	ds_read_b128 v[36:39], v134 offset:40960
	ds_read_b128 v[160:163], v135 offset:32768
	ds_read_b128 v[164:167], v135 offset:40960
	ds_read_b128 v[168:171], v136 offset:32768
	ds_read_b128 v[172:175], v136 offset:40960
	ds_read_b128 v[176:179], v137 offset:32768
	ds_read_b128 v[180:183], v137 offset:40960
	v_exp_f32_e32 v153, v153
	v_exp_f32_e32 v154, v154
	s_waitcnt lgkmcnt(7)
	v_mfma_f32_32x32x16_bf16 v[48:63], v[32:35], v[76:79], 0
	v_exp_f32_e32 v155, v155
	v_exp_f32_e32 v156, v156
	v_exp_f32_e32 v157, v157
	v_exp_f32_e32 v146, v146
	v_exp_f32_e32 v147, v147
	v_exp_f32_e32 v148, v148
	v_exp_f32_e32 v149, v149
	s_waitcnt lgkmcnt(6)
	v_mfma_f32_32x32x16_bf16 v[32:47], v[36:39], v[76:79], 0
	v_exp_f32_e32 v150, v150
	v_exp_f32_e32 v151, v151
	v_exp_f32_e32 v152, v152
	v_exp_f32_e32 v158, v158
	v_exp_f32_e32 v159, v159
	s_waitcnt lgkmcnt(5)
	v_mfma_f32_32x32x16_bf16 v[48:63], v[160:163], v[72:75], v[48:63]
	s_waitcnt lgkmcnt(4)
	v_mfma_f32_32x32x16_bf16 v[32:47], v[164:167], v[72:75], v[32:47]
	s_waitcnt lgkmcnt(3)
	v_mfma_f32_32x32x16_bf16 v[48:63], v[168:171], v[68:71], v[48:63]
	s_waitcnt lgkmcnt(2)
	v_mfma_f32_32x32x16_bf16 v[32:47], v[172:175], v[68:71], v[32:47]
	s_waitcnt lgkmcnt(1)
	v_mfma_f32_32x32x16_bf16 v[48:63], v[176:179], v[64:67], v[48:63]
	v_exp_f32_e32 v161, v144
	v_add_f32_e32 v144, 0, v96
	v_add_f32_e32 v144, v111, v144
	v_add_f32_e32 v144, v97, v144
	v_add_f32_e32 v144, v110, v144
	v_add_f32_e32 v144, v98, v144
	v_add_f32_e32 v144, v109, v144
	v_add_f32_e32 v144, v99, v144
	v_add_f32_e32 v144, v108, v144
	v_add_f32_e32 v144, v100, v144
	v_add_f32_e32 v144, v107, v144
	v_add_f32_e32 v144, v101, v144
	v_add_f32_e32 v144, v106, v144
	v_add_f32_e32 v144, v102, v144
	v_add_f32_e32 v144, v105, v144
	v_add_f32_e32 v144, v103, v144
	v_add_f32_e32 v144, v104, v144
	v_add_f32_e32 v144, v153, v144
	v_add_f32_e32 v144, v154, v144
	v_add_f32_e32 v144, v155, v144
	v_add_f32_e32 v144, v156, v144
	v_add_f32_e32 v144, v157, v144
	v_add_f32_e32 v144, v146, v144
	v_add_f32_e32 v144, v147, v144
	v_add_f32_e32 v144, v148, v144
	v_exp_f32_e32 v160, v145
	v_add_f32_e32 v144, v149, v144
	v_add_f32_e32 v144, v150, v144
	s_waitcnt lgkmcnt(0)
	v_mfma_f32_32x32x16_bf16 v[32:47], v[180:183], v[64:67], v[32:47]
	v_add_f32_e32 v144, v151, v144
	v_add_f32_e32 v144, v152, v144
	v_add_f32_e32 v144, v160, v144
	v_add_f32_e32 v144, v158, v144
	v_add_f32_e32 v144, v159, v144
	v_add_f32_e32 v144, v161, v144
	v_mov_b32_e32 v145, v144
	v_cvt_pk_bf16_f32 v96, v96, v111
	v_cvt_pk_bf16_f32 v97, v97, v110
	v_cvt_pk_bf16_f32 v98, v98, v109
	v_cvt_pk_bf16_f32 v99, v99, v108
	v_cvt_pk_bf16_f32 v100, v100, v107
	v_cvt_pk_bf16_f32 v101, v101, v106
	v_cvt_pk_bf16_f32 v102, v102, v105
	v_cvt_pk_bf16_f32 v103, v103, v104
	v_cvt_pk_bf16_f32 v104, v153, v154
	v_cvt_pk_bf16_f32 v105, v155, v156
	v_cvt_pk_bf16_f32 v106, v157, v146
	v_cvt_pk_bf16_f32 v107, v147, v148
	v_cvt_pk_bf16_f32 v108, v149, v150
	v_cvt_pk_bf16_f32 v109, v151, v152
	v_cvt_pk_bf16_f32 v110, v160, v158
	v_cvt_pk_bf16_f32 v111, v159, v161
	s_nop 1
	v_permlane32_swap_b32_e32 v144, v145
	v_permlane32_swap_b32_e32 v96, v98
	v_permlane32_swap_b32_e32 v97, v99
	v_permlane32_swap_b32_e32 v100, v102
	v_permlane32_swap_b32_e32 v101, v103
	v_permlane32_swap_b32_e32 v104, v106
	v_permlane32_swap_b32_e32 v105, v107
	v_permlane32_swap_b32_e32 v108, v110
	v_permlane32_swap_b32_e32 v109, v111
	s_cmp_gt_u32 s3, 12
	s_cselect_b64 s[80:81], -1, 0
	s_and_b64 vcc, exec, s[80:81]
	s_cbranch_vccnz .LBB0_823
	s_ashr_i32 s79, s78, 31
	v_lshl_add_u64 v[80:81], s[78:79], 0, v[114:115]
	v_mad_u64_u32 v[82:83], s[0:1], v80, s86, v[116:117]
	v_mad_u64_u32 v[84:85], s[0:1], v80, s86, v[118:119]
	v_mad_i32_i24 v83, v81, s86, v83
	v_mad_i32_i24 v85, v81, s86, v85
	global_load_dwordx4 v[80:83], v[82:83], off
	s_nop 0
	global_load_dwordx4 v[84:87], v[84:85], off
